# FFN up GEMM tail round: each of the 64 sample-row tiles is split into two 128-row half units on 128 workgroups (second-half MFMA blocks and epilogue rows skipped), no partial sums; prompt tiles remapp
# speedup vs baseline: 1.0137x; 1.0137x over previous
;     __host__ __device__ bool next(int i, Unit& u) const {
;         const long L = (long)i * G + c; if (L >= nwg) return false;
;         int wgid = (int)L; { const int q = nwg / NXCD, r = nwg % NXCD, xcd = wgid % NXCD, off = wgid / NXCD; wgid = (xcd < r ? xcd * (q + 1) : r * (q + 1) + (xcd - r) * q) + off; }
;         const int nig = WGM * nN, gid = wgid / nig, fm = gid * WGM, gsz = (nM - fm) < WGM ? (nM - fm) : WGM;
;         u.pm = fm + ((wgid % nig) % gsz); u.pn = (wgid % nig) / gsz; u.koff = 0; u.nt = nt0; return true;
.LBB0_1072:
	s_add_i32 s76, s76, 1
	s_mul_i32 s5, s76, s29
	s_mul_hi_u32 s10, s76, s28
	s_add_i32 s10, s10, s5
	s_mul_i32 s5, s76, s28
	s_add_u32 s14, s5, s2
	s_addc_u32 s15, s10, s23
	s_mov_b32 s100, 0
	s_cmpk_lt_i32 s14, 0x400
	s_cbranch_scc1 .Lup_sched_norm
	s_cmpk_lt_i32 s14, 0x480
	s_cbranch_scc1 .Lup_sched_half
	s_mov_b64 s[10:11], 0
	s_branch .LBB0_1074
.Lup_sched_half:
	s_sub_i32 s5, s14, 0x400
	s_and_b32 s100, s5, 1
	s_lshl_b32 s100, s100, 19
	s_lshr_b32 s5, s5, 1
	s_and_b32 s56, s5, 31
	s_lshr_b32 s5, s5, 5
	s_add_i32 s58, s5, 32
	s_mov_b64 s[10:11], -1
	s_branch .LBB0_1074

; template <class Epi, class Sched, bool ALIGN_EPI = false, bool SP2 = false>
; __device__ __forceinline__ void gemm_phase(PG8_LAS unsigned char* lds, const Gemm g, const Sched& S, const Epi& E) {
;     ...
;         const bool has_next = S.next(ui + 1, nxt);
;         const char* nA = has_next ? (const char*)g.A + (size_t)nxt.pm * tstep + nxt.koff : cA; const char* nB = has_next ? (const char*)g.Bt + (size_t)nxt.pn * tstep + nxt.koff : cB;
;         const int nt = cur.nt;
;         for (int t = 0; t < nt; t += 2) {
;             const bool last = (t == nt - 2);
;             const char* a1 = cA + (size_t)(t + 1) * kstep;
;     ...
;         for (int a = 0; a < 2; ++a)
; #pragma unroll
;             for (int b = 0; b < 2; ++b)
; #pragma unroll
;                 for (int m = 0; m < 4; ++m)
; #pragma unroll
;                     for (int n = 0; n < 2; ++n) acc[a][b][m][n] = (f32x4){0.f, 0.f, 0.f, 0.f};
.LBB0_1074:
	s_ashr_i32 s59, s58, 31
	s_lshl_b64 s[14:15], s[58:59], 20
	s_add_u32 s60, s53, s14
	s_addc_u32 s61, s54, s15
	s_add_u32 s60, s60, s100
	s_addc_u32 s61, s61, 0
	s_and_b64 s[14:15], s[10:11], exec
	s_cselect_b32 s5, s61, s37
	s_cselect_b32 s13, s60, s36
	s_ashr_i32 s57, s56, 31
	s_lshl_b64 s[14:15], s[56:57], 20
	s_add_u32 s62, s55, s14
	s_addc_u32 s63, s64, s15
	s_and_b64 s[14:15], s[10:11], exec
	s_cselect_b32 s14, s63, s45
	s_cselect_b32 s15, s62, s44
	s_add_u32 s36, s36, 0x80080
	s_addc_u32 s37, s37, 0
	s_add_u32 s57, s44, 0x100
	v_mov_b32_e32 v0, 0
	s_addc_u32 s59, s45, 0
	s_mov_b32 s80, -2
	s_add_i32 s101, s76, -1
	s_mul_i32 s101, s101, s28
	s_add_i32 s101, s101, s2
	s_cmpk_ge_i32 s101, 0x400
	s_cselect_b32 s101, 1, 0
	v_mov_b32_e32 v1, v0
	v_mov_b32_e32 v2, v0
	v_mov_b32_e32 v3, v0
	v_mov_b32_e32 v4, v0
	v_mov_b32_e32 v5, v0
	v_mov_b32_e32 v6, v0
	v_mov_b32_e32 v7, v0
	v_mov_b32_e32 v16, v0
	v_mov_b32_e32 v17, v0
	v_mov_b32_e32 v18, v0
	v_mov_b32_e32 v19, v0
	v_mov_b32_e32 v20, v0
	v_mov_b32_e32 v21, v0
	v_mov_b32_e32 v22, v0
	v_mov_b32_e32 v23, v0
	v_mov_b32_e32 v32, v0
	v_mov_b32_e32 v33, v0
	v_mov_b32_e32 v34, v0
	v_mov_b32_e32 v35, v0
	v_mov_b32_e32 v36, v0
	v_mov_b32_e32 v37, v0
	v_mov_b32_e32 v38, v0
	v_mov_b32_e32 v39, v0
	v_mov_b32_e32 v48, v0
	v_mov_b32_e32 v49, v0
	v_mov_b32_e32 v50, v0
	v_mov_b32_e32 v51, v0
	v_mov_b32_e32 v52, v0
	v_mov_b32_e32 v53, v0
	v_mov_b32_e32 v54, v0
	v_mov_b32_e32 v55, v0
	v_mov_b32_e32 v8, v0
	v_mov_b32_e32 v9, v0
	v_mov_b32_e32 v10, v0
	v_mov_b32_e32 v11, v0
	v_mov_b32_e32 v12, v0
	v_mov_b32_e32 v13, v0
	v_mov_b32_e32 v14, v0
	v_mov_b32_e32 v15, v0
	v_mov_b32_e32 v24, v0
	v_mov_b32_e32 v25, v0
	v_mov_b32_e32 v26, v0
	v_mov_b32_e32 v27, v0
	v_mov_b32_e32 v28, v0
	v_mov_b32_e32 v29, v0
	v_mov_b32_e32 v30, v0
	v_mov_b32_e32 v31, v0
	v_mov_b32_e32 v40, v0
	v_mov_b32_e32 v41, v0
	v_mov_b32_e32 v42, v0
	v_mov_b32_e32 v43, v0
	v_mov_b32_e32 v44, v0
	v_mov_b32_e32 v45, v0
	v_mov_b32_e32 v46, v0
	v_mov_b32_e32 v47, v0
	v_mov_b32_e32 v56, v0
	v_mov_b32_e32 v57, v0
	v_mov_b32_e32 v58, v0
	v_mov_b32_e32 v59, v0
	v_mov_b32_e32 v60, v0
	v_mov_b32_e32 v61, v0
	v_mov_b32_e32 v62, v0
	v_mov_b32_e32 v63, v0
	v_mov_b32_e32 v64, v0
	v_mov_b32_e32 v65, v0
	v_mov_b32_e32 v66, v0
	v_mov_b32_e32 v67, v0
	v_mov_b32_e32 v68, v0
	v_mov_b32_e32 v69, v0
	v_mov_b32_e32 v70, v0
	v_mov_b32_e32 v71, v0
	v_mov_b32_e32 v80, v0
	v_mov_b32_e32 v81, v0
	v_mov_b32_e32 v82, v0
	v_mov_b32_e32 v83, v0
	v_mov_b32_e32 v84, v0
	v_mov_b32_e32 v85, v0
	v_mov_b32_e32 v86, v0
	v_mov_b32_e32 v87, v0
	v_mov_b32_e32 v96, v0
	v_mov_b32_e32 v97, v0
	v_mov_b32_e32 v98, v0
	v_mov_b32_e32 v99, v0
	v_mov_b32_e32 v100, v0
	v_mov_b32_e32 v101, v0
	v_mov_b32_e32 v102, v0
	v_mov_b32_e32 v103, v0
	v_mov_b32_e32 v112, v0
	v_mov_b32_e32 v113, v0
	v_mov_b32_e32 v114, v0
	v_mov_b32_e32 v115, v0
	v_mov_b32_e32 v116, v0
	v_mov_b32_e32 v117, v0
	v_mov_b32_e32 v118, v0
	v_mov_b32_e32 v119, v0
	v_mov_b32_e32 v72, v0
	v_mov_b32_e32 v73, v0
	v_mov_b32_e32 v74, v0
	v_mov_b32_e32 v75, v0
	v_mov_b32_e32 v76, v0
	v_mov_b32_e32 v77, v0
	v_mov_b32_e32 v78, v0
	v_mov_b32_e32 v79, v0
	v_mov_b32_e32 v88, v0
	v_mov_b32_e32 v89, v0
	v_mov_b32_e32 v90, v0
	v_mov_b32_e32 v91, v0
	v_mov_b32_e32 v92, v0
	v_mov_b32_e32 v93, v0
	v_mov_b32_e32 v94, v0
	v_mov_b32_e32 v95, v0
	v_mov_b32_e32 v104, v0
	v_mov_b32_e32 v105, v0
	v_mov_b32_e32 v106, v0
	v_mov_b32_e32 v107, v0
	v_mov_b32_e32 v108, v0
	v_mov_b32_e32 v109, v0
	v_mov_b32_e32 v110, v0
	v_mov_b32_e32 v111, v0
	v_mov_b32_e32 v120, v0
	v_mov_b32_e32 v121, v0
	v_mov_b32_e32 v122, v0
	v_mov_b32_e32 v123, v0
	v_mov_b32_e32 v124, v0
	v_mov_b32_e32 v125, v0
	v_mov_b32_e32 v126, v0
	v_mov_b32_e32 v127, v0
.LBB0_1075:
	s_add_u32 s38, s36, 0xfff80080
	s_addc_u32 s39, s37, -1
	s_add_i32 s48, 0, 0x10000
	s_cmp_eq_u32 s80, 28
	s_cselect_b32 s47, s5, s39
	s_cselect_b32 s46, s13, s38
	v_add_u32_e32 v146, s48, v148
	s_cselect_b32 s45, s14, s59
	s_cselect_b32 s44, s15, s57
	s_add_i32 s49, 0, 0x14000
	ds_read_b128 v[142:145], v146
	ds_read_b128 v[152:155], v146 offset:1024
	ds_read_b128 v[156:159], v146 offset:2048
	ds_read_b128 v[160:163], v146 offset:3072
	v_add_u32_e32 v146, s49, v148
	ds_read_b128 v[164:167], v146
	ds_read_b128 v[168:171], v146 offset:1024
	ds_read_b128 v[172:175], v146 offset:2048
	ds_read_b128 v[176:179], v146 offset:3072
	v_lshl_add_u64 v[196:197], s[36:37], 0, v[138:139]
	s_add_i32 m0, s66, 0xc000
	ds_read_b128 v[180:183], v151
	ds_read_b128 v[184:187], v151 offset:1024
	ds_read_b128 v[188:191], v151 offset:2048
	ds_read_b128 v[198:201], v151 offset:3072
	ds_read_b128 v[202:205], v151 offset:4096
	ds_read_b128 v[206:209], v151 offset:5120
	ds_read_b128 v[210:213], v151 offset:6144
	ds_read_b128 v[214:217], v151 offset:7168
	global_load_lds_dwordx4 v[196:197], off
	v_lshl_add_u64 v[196:197], s[36:37], 0, v[140:141]
	s_add_i32 m0, s66, 0xe000
	s_nop 0
	global_load_lds_dwordx4 v[196:197], off
	s_waitcnt vmcnt(8)
	s_waitcnt lgkmcnt(0)
	s_barrier
; #define PG8_STAGE(bufoff, gbase, voff) do { _Pragma("unroll") for (int _i = 0; _i < 2; ++_i) \
;         __builtin_amdgcn_global_load_lds((const unsigned*)((const char*)(gbase) + (voff)[_i]), (PG8_LAS unsigned*)(lds + (bufoff) + ldsw + _i * 8192), 16, 0, 0); } while (0)
; #define PG8_LDA(dst, b, h) do { _Pragma("unroll") for (int m = 0; m < 4; ++m) _Pragma("unroll") for (int k = 0; k < 2; ++k) dst[m][k] = *(const PG8_LAS bf16x8*)(lds + PG8_SA(b, h) + aoff + m * 2048 + k * 1024); } while (0)
; #define PG8_LDB(dst, b, h) do { _Pragma("unroll") for (int n = 0; n < 2; ++n) _Pragma("unroll") for (int k = 0; k < 2; ++k) dst[n][k] = *(const PG8_LAS bf16x8*)(lds + PG8_SB(b, h) + boff + n * 2048 + k * 1024); } while (0)
; #define PG8_MMA(ai, bj, At, Bt) do { __builtin_amdgcn_s_setprio(1); _Pragma("unroll") for (int m = 0; m < 4; ++m) _Pragma("unroll") for (int n = 0; n < 2; ++n) _Pragma("unroll") for (int k = 0; k < 2; ++k) \
;         acc[ai][bj][m][n] = __builtin_amdgcn_mfma_f32_16x16x32_bf16(Bt[n][k], At[m][k], acc[ai][bj][m][n], 0, 0, 0); __builtin_amdgcn_s_setprio(0); } while (0)
; #define PG8_WAIT_V(n) asm volatile("s_waitcnt vmcnt(" #n ")" ::: "memory")
; #define PG8_WAIT_L(n) asm volatile("s_waitcnt lgkmcnt(" #n ")" ::: "memory")
; #define PG8_BAR __builtin_amdgcn_s_barrier()
; #define PG8_SCHED __builtin_amdgcn_sched_barrier(0)
; template <class Epi, class Sched, bool ALIGN_EPI = false, bool SP2 = false>
; __device__ __forceinline__ void gemm_phase(PG8_LAS unsigned char* lds, const Gemm g, const Sched& S, const Epi& E) {
;     ...
;             PG8_LDB(B0, 0, 0); PG8_LDB(B1, 0, 1); PG8_SCHED; PG8_LDA(At, 0, 0); PG8_STAGE(PG8_SA(1, 1), a1 + hstep, voffA);
;             PG8_WAIT_V(8); PG8_WAIT_L(0); PG8_BAR; PG8_MMA(0, 0, At, B0); PG8_MMA(0, 1, At, B1); PG8_BAR; PG8_SCHED;
;             PG8_LDA(At, 0, 1); PG8_STAGE(PG8_SB(0, 0), b2, voffB); PG8_STAGE(PG8_SB(0, 1), b2 + hstep, voffB); PG8_STAGE(PG8_SA(0, 0), a2, voffA);
	s_setprio 1
	s_waitcnt lgkmcnt(0)
	v_mfma_f32_16x16x32_bf16 v[124:127], v[142:145], v[180:183], v[124:127]
	v_mfma_f32_16x16x32_bf16 v[120:123], v[156:159], v[180:183], v[120:123]
	v_mfma_f32_16x16x32_bf16 v[108:111], v[142:145], v[188:191], v[108:111]
	v_mfma_f32_16x16x32_bf16 v[104:107], v[156:159], v[188:191], v[104:107]
	v_mfma_f32_16x16x32_bf16 v[92:95], v[142:145], v[202:205], v[92:95]
	v_mfma_f32_16x16x32_bf16 v[88:91], v[156:159], v[202:205], v[88:91]
	v_mfma_f32_16x16x32_bf16 v[76:79], v[142:145], v[210:213], v[76:79]
	v_mfma_f32_16x16x32_bf16 v[72:75], v[156:159], v[210:213], v[72:75]
	v_mfma_f32_16x16x32_bf16 v[124:127], v[152:155], v[184:187], v[124:127]
	v_mfma_f32_16x16x32_bf16 v[120:123], v[160:163], v[184:187], v[120:123]
	v_mfma_f32_16x16x32_bf16 v[108:111], v[152:155], v[198:201], v[108:111]
	v_mfma_f32_16x16x32_bf16 v[104:107], v[160:163], v[198:201], v[104:107]
	v_mfma_f32_16x16x32_bf16 v[92:95], v[152:155], v[206:209], v[92:95]
	v_mfma_f32_16x16x32_bf16 v[88:91], v[160:163], v[206:209], v[88:91]
	v_mfma_f32_16x16x32_bf16 v[76:79], v[152:155], v[214:217], v[76:79]
	v_mfma_f32_16x16x32_bf16 v[72:75], v[160:163], v[214:217], v[72:75]
	s_setprio 0
	s_setprio 1
	v_mfma_f32_16x16x32_bf16 v[116:119], v[164:167], v[180:183], v[116:119]
	v_mfma_f32_16x16x32_bf16 v[112:115], v[172:175], v[180:183], v[112:115]
	v_mfma_f32_16x16x32_bf16 v[100:103], v[164:167], v[188:191], v[100:103]
	v_mfma_f32_16x16x32_bf16 v[96:99], v[172:175], v[188:191], v[96:99]
	v_mfma_f32_16x16x32_bf16 v[84:87], v[164:167], v[202:205], v[84:87]
	v_mfma_f32_16x16x32_bf16 v[80:83], v[172:175], v[202:205], v[80:83]
	v_mfma_f32_16x16x32_bf16 v[68:71], v[164:167], v[210:213], v[68:71]
	v_mfma_f32_16x16x32_bf16 v[64:67], v[172:175], v[210:213], v[64:67]
	v_mfma_f32_16x16x32_bf16 v[116:119], v[168:171], v[184:187], v[116:119]
	v_mfma_f32_16x16x32_bf16 v[112:115], v[176:179], v[184:187], v[112:115]
	v_mfma_f32_16x16x32_bf16 v[100:103], v[168:171], v[198:201], v[100:103]
	v_mfma_f32_16x16x32_bf16 v[96:99], v[176:179], v[198:201], v[96:99]
	v_mfma_f32_16x16x32_bf16 v[84:87], v[168:171], v[206:209], v[84:87]
	v_mfma_f32_16x16x32_bf16 v[80:83], v[176:179], v[206:209], v[80:83]
	v_mfma_f32_16x16x32_bf16 v[68:71], v[168:171], v[214:217], v[68:71]
	v_mfma_f32_16x16x32_bf16 v[64:67], v[176:179], v[214:217], v[64:67]
	s_setprio 0
	s_barrier
	s_add_i32 s38, s48, s65
	v_lshl_add_u64 v[196:197], s[44:45], 0, v[130:131]
	s_mov_b32 m0, s38
	ds_read_b128 v[180:183], v151 offset:16384
	ds_read_b128 v[184:187], v151 offset:17408
	ds_read_b128 v[188:191], v151 offset:18432
	ds_read_b128 v[198:201], v151 offset:19456
	ds_read_b128 v[202:205], v151 offset:20480
	ds_read_b128 v[206:209], v151 offset:21504
	ds_read_b128 v[210:213], v151 offset:22528
	ds_read_b128 v[214:217], v151 offset:23552
	global_load_lds_dwordx4 v[196:197], off
	s_add_i32 m0, s38, 0x2000
	s_add_u32 s38, s44, 0x80000
	v_lshl_add_u64 v[224:225], s[44:45], 0, v[134:135]
	s_addc_u32 s39, s45, 0
	s_add_i32 s48, s49, s65
	global_load_lds_dwordx4 v[224:225], off
	v_lshl_add_u64 v[226:227], s[38:39], 0, v[130:131]
	s_mov_b32 m0, s48
	v_lshl_add_u64 v[236:237], s[46:47], 0, v[132:133]
	global_load_lds_dwordx4 v[226:227], off
	v_lshl_add_u64 v[226:227], s[38:39], 0, v[134:135]
	s_add_i32 m0, s48, 0x2000
	s_nop 0
	global_load_lds_dwordx4 v[226:227], off
	v_lshl_add_u64 v[226:227], s[46:47], 0, v[128:129]
	s_mov_b32 m0, s66
	s_nop 0
	global_load_lds_dwordx4 v[226:227], off
	s_mov_b32 m0, s67
	s_nop 0
	global_load_lds_dwordx4 v[236:237], off
	s_waitcnt vmcnt(8)
	s_waitcnt lgkmcnt(0)
	s_barrier
	s_setprio 1
	s_waitcnt lgkmcnt(0)
	s_cmp_eq_u32 s101, 1
	s_cbranch_scc1 .Lup_skip_sp2_0
	v_mfma_f32_16x16x32_bf16 v[60:63], v[142:145], v[180:183], v[60:63]
	v_mfma_f32_16x16x32_bf16 v[56:59], v[156:159], v[180:183], v[56:59]
	v_mfma_f32_16x16x32_bf16 v[44:47], v[142:145], v[188:191], v[44:47]
	v_mfma_f32_16x16x32_bf16 v[40:43], v[156:159], v[188:191], v[40:43]
	v_mfma_f32_16x16x32_bf16 v[28:31], v[142:145], v[202:205], v[28:31]
	v_mfma_f32_16x16x32_bf16 v[24:27], v[156:159], v[202:205], v[24:27]
	v_mfma_f32_16x16x32_bf16 v[12:15], v[142:145], v[210:213], v[12:15]
	v_mfma_f32_16x16x32_bf16 v[8:11], v[156:159], v[210:213], v[8:11]
	v_mfma_f32_16x16x32_bf16 v[60:63], v[152:155], v[184:187], v[60:63]
	v_mfma_f32_16x16x32_bf16 v[56:59], v[160:163], v[184:187], v[56:59]
	v_mfma_f32_16x16x32_bf16 v[44:47], v[152:155], v[198:201], v[44:47]
	v_mfma_f32_16x16x32_bf16 v[40:43], v[160:163], v[198:201], v[40:43]
	v_mfma_f32_16x16x32_bf16 v[28:31], v[152:155], v[206:209], v[28:31]
	v_mfma_f32_16x16x32_bf16 v[24:27], v[160:163], v[206:209], v[24:27]
	v_mfma_f32_16x16x32_bf16 v[12:15], v[152:155], v[214:217], v[12:15]
	v_mfma_f32_16x16x32_bf16 v[8:11], v[160:163], v[214:217], v[8:11]
	s_setprio 0
	s_setprio 1
	v_mfma_f32_16x16x32_bf16 v[52:55], v[164:167], v[180:183], v[52:55]
	v_mfma_f32_16x16x32_bf16 v[48:51], v[172:175], v[180:183], v[48:51]
	v_mfma_f32_16x16x32_bf16 v[36:39], v[164:167], v[188:191], v[36:39]
	v_mfma_f32_16x16x32_bf16 v[32:35], v[172:175], v[188:191], v[32:35]
	v_mfma_f32_16x16x32_bf16 v[20:23], v[164:167], v[202:205], v[20:23]
	v_mfma_f32_16x16x32_bf16 v[16:19], v[172:175], v[202:205], v[16:19]
	v_mfma_f32_16x16x32_bf16 v[4:7], v[164:167], v[210:213], v[4:7]
	v_mfma_f32_16x16x32_bf16 v[0:3], v[172:175], v[210:213], v[0:3]
	v_mfma_f32_16x16x32_bf16 v[52:55], v[168:171], v[184:187], v[52:55]
	v_mfma_f32_16x16x32_bf16 v[48:51], v[176:179], v[184:187], v[48:51]
	v_mfma_f32_16x16x32_bf16 v[36:39], v[168:171], v[198:201], v[36:39]
	v_mfma_f32_16x16x32_bf16 v[32:35], v[176:179], v[198:201], v[32:35]
	v_mfma_f32_16x16x32_bf16 v[20:23], v[168:171], v[206:209], v[20:23]
	v_mfma_f32_16x16x32_bf16 v[16:19], v[176:179], v[206:209], v[16:19]
	v_mfma_f32_16x16x32_bf16 v[4:7], v[168:171], v[214:217], v[4:7]
	v_mfma_f32_16x16x32_bf16 v[0:3], v[176:179], v[214:217], v[0:3]
; #define PG8_STAGE(bufoff, gbase, voff) do { _Pragma("unroll") for (int _i = 0; _i < 2; ++_i) \
;         __builtin_amdgcn_global_load_lds((const unsigned*)((const char*)(gbase) + (voff)[_i]), (PG8_LAS unsigned*)(lds + (bufoff) + ldsw + _i * 8192), 16, 0, 0); } while (0)
; #define PG8_LDA(dst, b, h) do { _Pragma("unroll") for (int m = 0; m < 4; ++m) _Pragma("unroll") for (int k = 0; k < 2; ++k) dst[m][k] = *(const PG8_LAS bf16x8*)(lds + PG8_SA(b, h) + aoff + m * 2048 + k * 1024); } while (0)
; #define PG8_LDB(dst, b, h) do { _Pragma("unroll") for (int n = 0; n < 2; ++n) _Pragma("unroll") for (int k = 0; k < 2; ++k) dst[n][k] = *(const PG8_LAS bf16x8*)(lds + PG8_SB(b, h) + boff + n * 2048 + k * 1024); } while (0)
; #define PG8_MMA(ai, bj, At, Bt) do { __builtin_amdgcn_s_setprio(1); _Pragma("unroll") for (int m = 0; m < 4; ++m) _Pragma("unroll") for (int n = 0; n < 2; ++n) _Pragma("unroll") for (int k = 0; k < 2; ++k) \
;         acc[ai][bj][m][n] = __builtin_amdgcn_mfma_f32_16x16x32_bf16(Bt[n][k], At[m][k], acc[ai][bj][m][n], 0, 0, 0); __builtin_amdgcn_s_setprio(0); } while (0)
; #define PG8_WAIT_V(n) asm volatile("s_waitcnt vmcnt(" #n ")" ::: "memory")
; #define PG8_WAIT_L(n) asm volatile("s_waitcnt lgkmcnt(" #n ")" ::: "memory")
; #define PG8_BAR __builtin_amdgcn_s_barrier()
; #define PG8_SCHED __builtin_amdgcn_sched_barrier(0)
; template <class Epi, class Sched, bool ALIGN_EPI = false, bool SP2 = false>
; __device__ __forceinline__ void gemm_phase(PG8_LAS unsigned char* lds, const Gemm g, const Sched& S, const Epi& E) {
;     ...
;             PG8_LDB(B0, 1, 0); PG8_LDB(B1, 1, 1); PG8_SCHED; PG8_LDA(At, 1, 0); PG8_STAGE(PG8_SA(0, 1), a2 + hstep, voffA);
;             PG8_WAIT_V(8); PG8_WAIT_L(0); PG8_BAR; PG8_MMA(0, 0, At, B0); PG8_MMA(0, 1, At, B1); PG8_BAR; PG8_SCHED;
.Lup_skip_sp2_0:
	s_setprio 0
	s_barrier
	s_add_i32 s48, 0, 0x18000
	v_add_u32_e32 v146, s48, v148
	s_add_i32 s49, 0, 0x1c000
	ds_read_b128 v[142:145], v146
	ds_read_b128 v[152:155], v146 offset:1024
	ds_read_b128 v[156:159], v146 offset:2048
	ds_read_b128 v[160:163], v146 offset:3072
	v_add_u32_e32 v146, s49, v148
	ds_read_b128 v[164:167], v146
	ds_read_b128 v[168:171], v146 offset:1024
	ds_read_b128 v[172:175], v146 offset:2048
	ds_read_b128 v[176:179], v146 offset:3072
	s_add_u32 s38, s46, 0x80000
	s_addc_u32 s39, s47, 0
	s_mov_b32 m0, s68
	v_lshl_add_u64 v[238:239], s[38:39], 0, v[128:129]
	ds_read_b128 v[180:183], v151 offset:32768
	ds_read_b128 v[184:187], v151 offset:33792
	ds_read_b128 v[188:191], v151 offset:34816
	ds_read_b128 v[198:201], v151 offset:35840
	ds_read_b128 v[202:205], v151 offset:36864
	ds_read_b128 v[206:209], v151 offset:37888
	ds_read_b128 v[210:213], v151 offset:38912
	ds_read_b128 v[214:217], v151 offset:39936
	global_load_lds_dwordx4 v[238:239], off
	v_lshl_add_u64 v[238:239], s[38:39], 0, v[132:133]
	s_mov_b32 m0, s70
	s_nop 0
	global_load_lds_dwordx4 v[238:239], off
	s_waitcnt vmcnt(8)
	s_waitcnt lgkmcnt(0)
	s_barrier
	s_setprio 1
	s_waitcnt lgkmcnt(0)
	v_mfma_f32_16x16x32_bf16 v[124:127], v[142:145], v[180:183], v[124:127]
	v_mfma_f32_16x16x32_bf16 v[120:123], v[156:159], v[180:183], v[120:123]
	v_mfma_f32_16x16x32_bf16 v[108:111], v[142:145], v[188:191], v[108:111]
	v_mfma_f32_16x16x32_bf16 v[104:107], v[156:159], v[188:191], v[104:107]
	v_mfma_f32_16x16x32_bf16 v[92:95], v[142:145], v[202:205], v[92:95]
	v_mfma_f32_16x16x32_bf16 v[88:91], v[156:159], v[202:205], v[88:91]
	v_mfma_f32_16x16x32_bf16 v[76:79], v[142:145], v[210:213], v[76:79]
	v_mfma_f32_16x16x32_bf16 v[72:75], v[156:159], v[210:213], v[72:75]
	v_mfma_f32_16x16x32_bf16 v[124:127], v[152:155], v[184:187], v[124:127]
	v_mfma_f32_16x16x32_bf16 v[120:123], v[160:163], v[184:187], v[120:123]
	v_mfma_f32_16x16x32_bf16 v[108:111], v[152:155], v[198:201], v[108:111]
	v_mfma_f32_16x16x32_bf16 v[104:107], v[160:163], v[198:201], v[104:107]
	v_mfma_f32_16x16x32_bf16 v[92:95], v[152:155], v[206:209], v[92:95]
	v_mfma_f32_16x16x32_bf16 v[88:91], v[160:163], v[206:209], v[88:91]
	v_mfma_f32_16x16x32_bf16 v[76:79], v[152:155], v[214:217], v[76:79]
	v_mfma_f32_16x16x32_bf16 v[72:75], v[160:163], v[214:217], v[72:75]
	s_setprio 0
	s_setprio 1
	v_mfma_f32_16x16x32_bf16 v[116:119], v[164:167], v[180:183], v[116:119]
	v_mfma_f32_16x16x32_bf16 v[112:115], v[172:175], v[180:183], v[112:115]
	v_mfma_f32_16x16x32_bf16 v[100:103], v[164:167], v[188:191], v[100:103]
	v_mfma_f32_16x16x32_bf16 v[96:99], v[172:175], v[188:191], v[96:99]
	v_mfma_f32_16x16x32_bf16 v[84:87], v[164:167], v[202:205], v[84:87]
	v_mfma_f32_16x16x32_bf16 v[80:83], v[172:175], v[202:205], v[80:83]
	v_mfma_f32_16x16x32_bf16 v[68:71], v[164:167], v[210:213], v[68:71]
	v_mfma_f32_16x16x32_bf16 v[64:67], v[172:175], v[210:213], v[64:67]
	v_mfma_f32_16x16x32_bf16 v[116:119], v[168:171], v[184:187], v[116:119]
	v_mfma_f32_16x16x32_bf16 v[112:115], v[176:179], v[184:187], v[112:115]
	v_mfma_f32_16x16x32_bf16 v[100:103], v[168:171], v[198:201], v[100:103]
	v_mfma_f32_16x16x32_bf16 v[96:99], v[176:179], v[198:201], v[96:99]
	v_mfma_f32_16x16x32_bf16 v[84:87], v[168:171], v[206:209], v[84:87]
	v_mfma_f32_16x16x32_bf16 v[80:83], v[176:179], v[206:209], v[80:83]
	v_mfma_f32_16x16x32_bf16 v[68:71], v[168:171], v[214:217], v[68:71]
	v_mfma_f32_16x16x32_bf16 v[64:67], v[176:179], v[214:217], v[64:67]
	s_setprio 0
	s_barrier
; #define PG8_STAGE(bufoff, gbase, voff) do { _Pragma("unroll") for (int _i = 0; _i < 2; ++_i) \
;         __builtin_amdgcn_global_load_lds((const unsigned*)((const char*)(gbase) + (voff)[_i]), (PG8_LAS unsigned*)(lds + (bufoff) + ldsw + _i * 8192), 16, 0, 0); } while (0)
; #define PG8_LDA(dst, b, h) do { _Pragma("unroll") for (int m = 0; m < 4; ++m) _Pragma("unroll") for (int k = 0; k < 2; ++k) dst[m][k] = *(const PG8_LAS bf16x8*)(lds + PG8_SA(b, h) + aoff + m * 2048 + k * 1024); } while (0)
; #define PG8_MMA(ai, bj, At, Bt) do { __builtin_amdgcn_s_setprio(1); _Pragma("unroll") for (int m = 0; m < 4; ++m) _Pragma("unroll") for (int n = 0; n < 2; ++n) _Pragma("unroll") for (int k = 0; k < 2; ++k) \
;         acc[ai][bj][m][n] = __builtin_amdgcn_mfma_f32_16x16x32_bf16(Bt[n][k], At[m][k], acc[ai][bj][m][n], 0, 0, 0); __builtin_amdgcn_s_setprio(0); } while (0)
; #define PG8_WAIT_V(n) asm volatile("s_waitcnt vmcnt(" #n ")" ::: "memory")
; #define PG8_WAIT_L(n) asm volatile("s_waitcnt lgkmcnt(" #n ")" ::: "memory")
; #define PG8_BAR __builtin_amdgcn_s_barrier()
; #define PG8_SCHED __builtin_amdgcn_sched_barrier(0)
; template <class Epi, class Sched, bool ALIGN_EPI = false, bool SP2 = false>
; __device__ __forceinline__ void gemm_phase(PG8_LAS unsigned char* lds, const Gemm g, const Sched& S, const Epi& E) {
;     ...
;             PG8_LDA(At, 1, 1); PG8_STAGE(PG8_SB(1, 0), b3, voffB); PG8_STAGE(PG8_SB(1, 1), b3 + hstep, voffB); PG8_STAGE(PG8_SA(1, 0), a3, voffA);
;             PG8_WAIT_V(8); PG8_WAIT_L(0); PG8_BAR; PG8_MMA(1, 0, At, B0); PG8_MMA(1, 1, At, B1); PG8_BAR; PG8_SCHED;
;     __device__ __forceinline__ void operator()(const f32x4 (&acc)[2][2][4][2], const pg8::Unit& u, int wr, int wc, int fr, int fq) const {
;     ...
;         const int pn = u.pn, rowb = u.pm * 256 + wr * 64 + fr, cl = wc * 32 + 8 * fq;
	s_add_i32 s38, s48, s65
	v_lshl_add_u64 v[196:197], v[196:197], 0, s[78:79]
	s_mov_b32 m0, s38
	ds_read_b128 v[180:183], v151 offset:49152
	ds_read_b128 v[184:187], v151 offset:50176
	ds_read_b128 v[188:191], v151 offset:51200
	ds_read_b128 v[198:201], v151 offset:52224
	ds_read_b128 v[202:205], v151 offset:53248
	ds_read_b128 v[206:209], v151 offset:54272
	ds_read_b128 v[210:213], v151 offset:55296
	ds_read_b128 v[214:217], v151 offset:56320
	global_load_lds_dwordx4 v[196:197], off
	s_add_i32 m0, s38, 0x2000
	s_add_u32 s38, s44, 0x80080
	v_lshl_add_u64 v[196:197], v[224:225], 0, s[78:79]
	s_addc_u32 s39, s45, 0
	s_add_i32 s44, s49, s65
	global_load_lds_dwordx4 v[196:197], off
	v_lshl_add_u64 v[196:197], s[38:39], 0, v[130:131]
	s_mov_b32 m0, s44
	s_nop 0
	global_load_lds_dwordx4 v[196:197], off
	v_lshl_add_u64 v[196:197], s[38:39], 0, v[134:135]
	s_add_i32 m0, s44, 0x2000
	s_nop 0
	global_load_lds_dwordx4 v[196:197], off
	v_lshl_add_u64 v[196:197], v[226:227], 0, s[78:79]
	s_mov_b32 m0, s72
	s_nop 0
	global_load_lds_dwordx4 v[196:197], off
	v_lshl_add_u64 v[196:197], v[236:237], 0, s[78:79]
	s_mov_b32 m0, s73
	s_nop 0
	global_load_lds_dwordx4 v[196:197], off
	s_waitcnt vmcnt(8)
	s_waitcnt lgkmcnt(0)
	s_barrier
	s_setprio 1
	s_waitcnt lgkmcnt(0)
	s_cmp_eq_u32 s101, 1
	s_cbranch_scc1 .Lup_skip_sp2_1
	v_mfma_f32_16x16x32_bf16 v[60:63], v[142:145], v[180:183], v[60:63]
	v_mfma_f32_16x16x32_bf16 v[56:59], v[156:159], v[180:183], v[56:59]
	v_mfma_f32_16x16x32_bf16 v[44:47], v[142:145], v[188:191], v[44:47]
	v_mfma_f32_16x16x32_bf16 v[40:43], v[156:159], v[188:191], v[40:43]
	v_mfma_f32_16x16x32_bf16 v[28:31], v[142:145], v[202:205], v[28:31]
	v_mfma_f32_16x16x32_bf16 v[24:27], v[156:159], v[202:205], v[24:27]
	v_mfma_f32_16x16x32_bf16 v[12:15], v[142:145], v[210:213], v[12:15]
	v_mfma_f32_16x16x32_bf16 v[8:11], v[156:159], v[210:213], v[8:11]
	v_mfma_f32_16x16x32_bf16 v[60:63], v[152:155], v[184:187], v[60:63]
	v_mfma_f32_16x16x32_bf16 v[56:59], v[160:163], v[184:187], v[56:59]
	v_mfma_f32_16x16x32_bf16 v[44:47], v[152:155], v[198:201], v[44:47]
	v_mfma_f32_16x16x32_bf16 v[40:43], v[160:163], v[198:201], v[40:43]
	v_mfma_f32_16x16x32_bf16 v[28:31], v[152:155], v[206:209], v[28:31]
	v_mfma_f32_16x16x32_bf16 v[24:27], v[160:163], v[206:209], v[24:27]
	v_mfma_f32_16x16x32_bf16 v[12:15], v[152:155], v[214:217], v[12:15]
	v_mfma_f32_16x16x32_bf16 v[8:11], v[160:163], v[214:217], v[8:11]
	s_setprio 0
	s_setprio 1
	v_mfma_f32_16x16x32_bf16 v[52:55], v[164:167], v[180:183], v[52:55]
	v_mfma_f32_16x16x32_bf16 v[48:51], v[172:175], v[180:183], v[48:51]
	v_mfma_f32_16x16x32_bf16 v[36:39], v[164:167], v[188:191], v[36:39]
	v_mfma_f32_16x16x32_bf16 v[32:35], v[172:175], v[188:191], v[32:35]
	v_mfma_f32_16x16x32_bf16 v[20:23], v[164:167], v[202:205], v[20:23]
	v_mfma_f32_16x16x32_bf16 v[16:19], v[172:175], v[202:205], v[16:19]
	v_mfma_f32_16x16x32_bf16 v[4:7], v[164:167], v[210:213], v[4:7]
	v_mfma_f32_16x16x32_bf16 v[0:3], v[172:175], v[210:213], v[0:3]
	v_mfma_f32_16x16x32_bf16 v[52:55], v[168:171], v[184:187], v[52:55]
	v_mfma_f32_16x16x32_bf16 v[48:51], v[176:179], v[184:187], v[48:51]
	v_mfma_f32_16x16x32_bf16 v[36:39], v[168:171], v[198:201], v[36:39]
	v_mfma_f32_16x16x32_bf16 v[32:35], v[176:179], v[198:201], v[32:35]
	v_mfma_f32_16x16x32_bf16 v[20:23], v[168:171], v[206:209], v[20:23]
	v_mfma_f32_16x16x32_bf16 v[16:19], v[176:179], v[206:209], v[16:19]
	v_mfma_f32_16x16x32_bf16 v[4:7], v[168:171], v[214:217], v[4:7]
	v_mfma_f32_16x16x32_bf16 v[0:3], v[176:179], v[214:217], v[0:3]
.Lup_skip_sp2_1:
	s_setprio 0
	s_barrier
	s_add_i32 s80, s80, 2
	s_add_u32 s36, s36, 0x100
	s_addc_u32 s37, s37, 0
	s_add_u32 s57, s57, 0x100
	s_addc_u32 s59, s59, 0
	s_cmp_gt_u32 s80, 29
	s_cbranch_scc0 .LBB0_1075
	s_and_b64 vcc, exec, s[30:31]
	s_cbranch_vccz .LBB0_1078
	s_barrier
.LBB0_1078:
	s_add_i32 s100, s76, -1
	s_mul_i32 s100, s100, s28
	s_add_i32 s100, s100, s2
	s_and_b32 s100, s100, s101
	s_lshl_b32 s100, s100, 7
	s_lshl_b32 s14, s12, 8
	s_add_i32 s14, s14, s71
	s_add_i32 s14, s14, s100
	v_or_b32_e32 v142, s14, v147
	v_ashrrev_i32_e32 v143, 31, v142
	v_lshlrev_b64 v[144:145], 8, v[142:143]
	v_lshl_add_u64 v[144:145], v[136:137], 0, v[144:145]
	v_mov_b32_e32 v146, 0
	s_mov_b32 s5, s77

;     __device__ __forceinline__ void operator()(const f32x4 (&acc)[2][2][4][2], const pg8::Unit& u, int wr, int wc, int fr, int fq) const {
;     ...
;             for (int ai = 0; ai < 2; ++ai)
; #pragma unroll
;                 for (int m = 0; m < 4; ++m) {
.LBB0_1096:
	s_or_b64 exec, exec, s[4:5]
	s_cmp_eq_u32 s101, 1
	s_cbranch_scc1 .Lup_ep_done
	s_nop 0
	v_add_u32_e32 v64, 0x80, v142
	v_ashrrev_i32_e32 v65, 31, v64
	v_lshlrev_b64 v[66:67], 8, v[64:65]
	v_lshl_add_u64 v[66:67], v[136:137], 0, v[66:67]
	v_mov_b32_e32 v68, 0
	s_mov_b32 s4, s77
